# pp_v20 + DPP butterflies (quad_perm / row_half_mirror adds) replace the xor-1/2/4 ds_bpermute reductions in RC1 S0c and the PR1 group-norm loop
# baseline (speedup 1.0000x reference)
.Lrc_nopf:
	v_and_b32_e32 v101, 0xffff0000, v42
	v_lshlrev_b32_e32 v100, 16, v42
	v_pk_add_f32 v[194:195], v[194:195], v[196:197] neg_lo:[0,1] neg_hi:[0,1]
	v_lshlrev_b32_e32 v30, 16, v27
	s_waitcnt lgkmcnt(8)
	v_pk_fma_f32 v[70:71], v[194:195], v[70:71], v[196:197]
	v_pk_add_f32 v[194:195], v[100:101], -1.0 op_sel_hi:[1,0]
	s_waitcnt lgkmcnt(5)
	v_mul_f32_e32 v78, v70, v78
	s_waitcnt lgkmcnt(3)
	v_pk_fma_f32 v[74:75], v[194:195], v[74:75], 1.0 op_sel_hi:[1,1,0]
	v_mul_f32_e32 v1, v71, v79
	v_pk_mul_f32 v[70:71], v[70:71], v[74:75]
	v_mul_f32_e32 v79, v1, v1
	v_pk_mul_f32 v[74:75], v[82:83], v[70:71]
	v_fmac_f32_e32 v79, v78, v78
	s_waitcnt lgkmcnt(1)
	v_pk_mul_f32 v[66:67], v[66:67], v[74:75]
	v_and_b32_e32 v75, 0xffff0000, v31
	v_add_f32_e32 v26, 0, v66
	v_add_f32_e32 v42, v67, v26
	v_lshlrev_b32_e32 v74, 16, v31
	v_and_b32_e32 v31, 0xffff0000, v27
	v_and_b32_e32 v27, 0xffff0000, v39
	v_lshlrev_b32_e32 v26, 16, v39
	v_pk_add_f32 v[26:27], v[26:27], v[74:75] neg_lo:[0,1] neg_hi:[0,1]
	v_and_b32_e32 v67, 0xffff0000, v43
	v_pk_fma_f32 v[38:39], v[26:27], v[84:85], v[74:75]
	v_and_b32_e32 v27, 0xffff0000, v35
	v_lshlrev_b32_e32 v26, 16, v35
	v_lshlrev_b32_e32 v66, 16, v43
	v_pk_add_f32 v[26:27], v[26:27], v[30:31] neg_lo:[0,1] neg_hi:[0,1]
	v_and_b32_e32 v43, 0xffff0000, v40
	v_pk_fma_f32 v[26:27], v[26:27], v[72:73], v[30:31]
	v_pk_add_f32 v[30:31], v[66:67], -1.0 op_sel_hi:[1,0]
	v_mul_f32_e32 v73, v26, v80
	v_pk_fma_f32 v[30:31], v[30:31], v[76:77], 1.0 op_sel_hi:[1,1,0]
	v_mul_f32_e32 v72, v27, v81
	v_pk_mul_f32 v[34:35], v[26:27], v[30:31]
	v_and_b32_e32 v31, 0xffff0000, v28
	v_pk_mul_f32 v[26:27], v[38:39], v[34:35]
	v_lshlrev_b32_e32 v30, 16, v28
	v_pk_mul_f32 v[26:27], v[68:69], v[26:27]
	v_and_b32_e32 v69, 0xffff0000, v44
	v_add_f32_e32 v26, v26, v42
	v_add_f32_e32 v74, v27, v26
	v_and_b32_e32 v27, 0xffff0000, v32
	v_lshlrev_b32_e32 v26, 16, v32
	v_lshlrev_b32_e32 v42, 16, v40
	v_pk_add_f32 v[42:43], v[42:43], v[26:27] neg_lo:[0,1] neg_hi:[0,1]
	v_lshlrev_b32_e32 v68, 16, v44
	v_pk_fma_f32 v[54:55], v[42:43], v[54:55], v[26:27]
	v_and_b32_e32 v27, 0xffff0000, v36
	v_lshlrev_b32_e32 v26, 16, v36
	v_pk_add_f32 v[26:27], v[26:27], v[30:31] neg_lo:[0,1] neg_hi:[0,1]
	v_lshlrev_b32_e32 v32, 16, v29
	v_pk_fma_f32 v[26:27], v[26:27], v[50:51], v[30:31]
	v_pk_add_f32 v[30:31], v[68:69], -1.0 op_sel_hi:[1,0]
	v_mul_f32_e32 v44, v26, v46
	v_pk_fma_f32 v[30:31], v[30:31], v[62:63], 1.0 op_sel_hi:[1,1,0]
	v_mul_f32_e32 v40, v27, v47
	v_pk_mul_f32 v[42:43], v[26:27], v[30:31]
	v_lshlrev_b32_e32 v28, 16, v41
	v_pk_mul_f32 v[26:27], v[54:55], v[42:43]
	v_and_b32_e32 v31, 0xffff0000, v45
	s_waitcnt lgkmcnt(0)
	v_pk_mul_f32 v[26:27], v[58:59], v[26:27]
	v_lshlrev_b32_e32 v30, 16, v45
	v_add_f32_e32 v26, v26, v74
	v_add_f32_e32 v36, v27, v26
	v_and_b32_e32 v27, 0xffff0000, v33
	v_lshlrev_b32_e32 v26, 16, v33
	v_and_b32_e32 v33, 0xffff0000, v29
	v_and_b32_e32 v29, 0xffff0000, v41
	v_pk_add_f32 v[28:29], v[28:29], v[26:27] neg_lo:[0,1] neg_hi:[0,1]
	v_fmac_f32_e32 v79, v73, v73
	v_pk_fma_f32 v[26:27], v[28:29], v[56:57], v[26:27]
	v_and_b32_e32 v29, 0xffff0000, v37
	v_lshlrev_b32_e32 v28, 16, v37
	v_pk_add_f32 v[28:29], v[28:29], v[32:33] neg_lo:[0,1] neg_hi:[0,1]
	v_fmac_f32_e32 v79, v72, v72
	v_pk_fma_f32 v[32:33], v[28:29], v[52:53], v[32:33]
	v_pk_add_f32 v[28:29], v[30:31], -1.0 op_sel_hi:[1,0]
	v_mul_f32_e32 v37, v32, v48
	v_pk_fma_f32 v[28:29], v[28:29], v[64:65], 1.0 op_sel_hi:[1,1,0]
	v_fmac_f32_e32 v79, v44, v44
	v_pk_mul_f32 v[28:29], v[32:33], v[28:29]
	v_fmac_f32_e32 v79, v40, v40
	v_pk_mul_f32 v[46:47], v[26:27], v[28:29]
	v_fmac_f32_e32 v79, v37, v37
	v_pk_mul_f32 v[46:47], v[60:61], v[46:47]
	v_lshl_add_u32 v88, v110, 2, s47
	v_add_f32_e32 v32, v46, v36
	v_add_f32_e32 v32, v47, v32
	v_mul_f32_e32 v36, v33, v49
	v_fmac_f32_e32 v79, v36, v36
	v_lshlrev_b32_e32 v58, 16, v18
	ds_read_b32 v41, v88
	ds_read_b128 v[48:51], v167 offset:80
	v_add_f32_dpp v32, v32, v32 quad_perm:[1,0,3,2] row_mask:0xf bank_mask:0xf
	v_add_f32_dpp v33, v79, v79 quad_perm:[1,0,3,2] row_mask:0xf bank_mask:0xf
	v_and_b32_e32 v59, 0xffff0000, v18
	v_lshlrev_b32_e32 v18, 16, v19
	v_add_f32_dpp v32, v32, v32 quad_perm:[2,3,0,1] row_mask:0xf bank_mask:0xf
	v_add_f32_dpp v33, v33, v33 quad_perm:[2,3,0,1] row_mask:0xf bank_mask:0xf
	v_and_b32_e32 v19, 0xffff0000, v19
	s_nop 0
	v_add_f32_dpp v52, v32, v32 row_half_mirror row_mask:0xf bank_mask:0xf
	v_add_f32_dpp v53, v33, v33 row_half_mirror row_mask:0xf bank_mask:0xf
	v_and_b32_e32 v33, 0xffff0000, v14
	v_lshlrev_b32_e32 v32, 16, v14
	v_lshlrev_b32_e32 v14, 16, v15
	v_and_b32_e32 v15, 0xffff0000, v15
	v_pk_add_f32 v[58:59], v[58:59], v[32:33] neg_lo:[0,1] neg_hi:[0,1]
	v_pk_add_f32 v[18:19], v[18:19], v[14:15] neg_lo:[0,1] neg_hi:[0,1]
	v_pk_fma_f32 v[32:33], v[58:59], v[22:23], v[32:33]
	v_pk_fma_f32 v[22:23], v[18:19], v[24:25], v[14:15]
	v_lshlrev_b32_e32 v14, 16, v16
	v_and_b32_e32 v15, 0xffff0000, v16
	v_lshlrev_b32_e32 v18, 16, v20
	v_and_b32_e32 v19, 0xffff0000, v20
	v_pk_add_f32 v[18:19], v[18:19], v[14:15] neg_lo:[0,1] neg_hi:[0,1]
	ds_read_b32 v45, v115
	s_waitcnt lgkmcnt(1)
	v_pk_fma_f32 v[18:19], v[18:19], v[48:49], v[14:15]
	v_lshlrev_b32_e32 v14, 16, v17
	v_and_b32_e32 v15, 0xffff0000, v17
	v_lshlrev_b32_e32 v16, 16, v21
	v_and_b32_e32 v17, 0xffff0000, v21
	v_pk_add_f32 v[16:17], v[16:17], v[14:15] neg_lo:[0,1] neg_hi:[0,1]
	v_pk_mul_f32 v[58:59], v[32:33], v[52:53] op_sel_hi:[1,0]
	v_pk_fma_f32 v[14:15], v[16:17], v[50:51], v[14:15]
	v_pk_mul_f32 v[24:25], v[22:23], v[52:53] op_sel_hi:[1,0]
	v_pk_mul_f32 v[60:61], v[18:19], v[52:53] op_sel_hi:[1,0]
	v_pk_mul_f32 v[16:17], v[14:15], v[52:53] op_sel_hi:[1,0]
	v_mov_b32_e32 v46, 0
	v_cvt_pk_bf16_f32 v48, v58, v59
	v_cvt_pk_bf16_f32 v49, v24, v25
	v_cvt_pk_bf16_f32 v50, v60, v61
	v_cvt_pk_bf16_f32 v51, v16, v17
	v_mov_b32_e32 v20, 0
	global_store_dwordx4 v[102:103], v[48:51], off
	v_mov_b32_e32 v25, 0
	v_mov_b32_e32 v52, 0
	v_mov_b32_e32 v59, 0
	v_mov_b32_e32 v62, 0
	v_mov_b32_e32 v47, 0
	v_mov_b32_e32 v65, 0
	s_and_saveexec_b64 s[0:1], s[4:5]
	ds_read_b32 v228, v116
	ds_read_b32 v229, v116 offset:4
	ds_read_b32 v230, v116 offset:8
	ds_read_b32 v231, v116 offset:12
	ds_read_b32 v232, v116 offset:16
	ds_read_b32 v233, v116 offset:20
	ds_read_b32 v234, v116 offset:24
	ds_read_b32 v235, v116 offset:28
	s_or_b64 exec, exec, s[0:1]
	ds_read_b32 v16, v115 offset:4
	ds_read_b32 v17, v88 offset:4
	ds_read_b32 v21, v115 offset:8
	ds_read_b32 v24, v88 offset:8
	s_waitcnt lgkmcnt(4)
	s_and_saveexec_b64 s[0:1], s[4:5]
	v_mul_f32_e32 v20, 0x3fb8aa3b, v228
	v_mul_f32_e32 v46, 0x3fb8aa3b, v229
	v_mul_f32_e32 v52, 0x3fb8aa3b, v230
	v_mul_f32_e32 v25, 0x3fb8aa3b, v231
	v_mul_f32_e32 v62, 0x3fb8aa3b, v232
	v_mul_f32_e32 v59, 0x3fb8aa3b, v233
	v_mul_f32_e32 v65, 0x3fb8aa3b, v234
	v_mul_f32_e32 v47, 0x3fb8aa3b, v235
	s_or_b64 exec, exec, s[0:1]
	ds_read_b32 v48, v115 offset:12
	ds_read_b32 v49, v88 offset:12
	ds_read_b32 v57, v115 offset:16
	ds_read_b32 v58, v88 offset:16
	ds_read_b32 v60, v115 offset:20
	ds_read_b32 v61, v88 offset:20
	ds_read_b32 v63, v115 offset:24
	ds_read_b32 v64, v88 offset:24
	ds_read_b32 v50, v115 offset:28
	ds_read_b32 v51, v88 offset:28
	s_waitcnt lgkmcnt(14)
	s_mov_b32 s0, 0xf800000
	v_mul_f32_e32 v56, 0x4f800000, v53
	v_cmp_gt_f32_e32 vcc, s0, v53
	v_exp_f32_e32 v65, v65
	v_exp_f32_e32 v62, v62
	v_cndmask_b32_e32 v53, v53, v56, vcc
	v_sqrt_f32_e32 v56, v53
	v_exp_f32_e32 v59, v59
	v_exp_f32_e32 v52, v52
	v_exp_f32_e32 v20, v20
	v_add_u32_e32 v74, -1, v56
	v_fma_f32 v76, -v74, v56, v53
	v_add_u32_e32 v75, 1, v56
	v_cmp_ge_f32_e64 s[0:1], 0, v76
	v_exp_f32_e32 v25, v25
	v_exp_f32_e32 v46, v46
	v_cndmask_b32_e64 v74, v56, v74, s[0:1]
	v_fma_f32 v56, -v75, v56, v53
	v_cmp_lt_f32_e64 s[0:1], 0, v56
	v_exp_f32_e32 v47, v47
	v_sub_f32_e32 v41, v41, v45
	v_cndmask_b32_e64 v56, v74, v75, s[0:1]
	v_mul_f32_e32 v74, 0x37800000, v56
	v_cndmask_b32_e32 v56, v56, v74, vcc
	v_cmp_class_f32_e32 vcc, v53, v168
	v_mul_f32_e32 v41, 0x3fb8aa3b, v41
	v_exp_f32_e32 v41, v41
	v_cndmask_b32_e32 v53, v56, v53, vcc
	v_max_f32_e32 v53, 0x2b8cbccc, v53
	v_div_scale_f32 v56, s[0:1], v53, v53, 1.0
	v_rcp_f32_e32 v74, v56
	s_nop 0
	v_fma_f32 v75, -v56, v74, 1.0
	v_fmac_f32_e32 v74, v75, v74
	v_div_scale_f32 v75, vcc, 1.0, v53, 1.0
	v_mul_f32_e32 v76, v75, v74
	v_fma_f32 v77, -v56, v76, v75
	v_fmac_f32_e32 v76, v77, v74
	v_fma_f32 v56, -v56, v76, v75
	v_div_fmas_f32 v56, v56, v74, v76
	v_div_fixup_f32 v53, v56, v53, 1.0
	s_waitcnt lgkmcnt(3)
	v_mul_f32_e32 v56, 0x3fb8aa3b, v63
	v_mul_f32_e32 v74, 0xbfb8aa3b, v63
	s_waitcnt lgkmcnt(2)
	v_sub_f32_e32 v63, v64, v63
	v_mul_f32_e32 v63, 0x3fb8aa3b, v63
	v_exp_f32_e32 v56, v56
	v_exp_f32_e32 v74, v74
	v_exp_f32_e32 v63, v63
	v_mul_f32_e32 v37, v37, v53
	v_mul_f32_e32 v30, v37, v30
	v_mul_f32_e32 v37, v37, v65
	v_mul_f32_e32 v56, v26, v56
	v_mul_f32_e32 v64, v30, v74
	v_mul_f32_e32 v65, v28, v74
	v_mul_f32_e32 v30, v30, v63
	v_mul_f32_e32 v28, v28, v63
	v_mul_f32_e32 v26, v44, v53
	v_mul_f32_e32 v44, 0x3fb8aa3b, v57
	v_mul_f32_e32 v63, 0xbfb8aa3b, v57
	v_exp_f32_e32 v44, v44
	v_exp_f32_e32 v63, v63
	v_mul_f32_e32 v68, v26, v68
	v_mul_f32_e32 v40, v40, v53
	v_mul_f32_e32 v26, v26, v62
	v_mul_f32_e32 v44, v54, v44
	v_mul_f32_e32 v54, v68, v63
	v_mul_f32_e32 v62, v42, v63
	v_mul_f32_e32 v63, v40, v69
	v_mul_f32_e32 v69, 0x3fb8aa3b, v60
	v_mul_f32_e32 v74, 0xbfb8aa3b, v60
	v_sub_f32_e32 v60, v61, v60
	v_sub_f32_e32 v57, v58, v57
	v_mul_f32_e32 v60, 0x3fb8aa3b, v60
	v_mul_f32_e32 v57, 0x3fb8aa3b, v57
	v_exp_f32_e32 v74, v74
	v_exp_f32_e32 v60, v60
	v_exp_f32_e32 v57, v57
	v_mul_f32_e32 v40, v40, v59
	v_mul_f32_e32 v59, v63, v74
	v_mul_f32_e32 v58, v43, v74
	v_mul_f32_e32 v61, v63, v60
	v_mul_f32_e32 v43, v43, v60
	v_mul_f32_e32 v60, v68, v57
	v_mul_f32_e32 v63, 0x3fb8aa3b, v21
	v_mul_f32_e32 v68, 0xbfb8aa3b, v21
	v_exp_f32_e32 v69, v69
	v_exp_f32_e32 v63, v63
	v_exp_f32_e32 v68, v68
	v_mul_f32_e32 v42, v42, v57
	v_mul_f32_e32 v57, v73, v53
	v_mul_f32_e32 v66, v57, v66
	v_mul_f32_e32 v55, v55, v69
	v_mul_f32_e32 v52, v57, v52
	v_mul_f32_e32 v38, v38, v63
	v_mul_f32_e32 v57, v66, v68
	v_mul_f32_e32 v63, v34, v68
	v_mul_f32_e32 v68, v72, v53
	v_mul_f32_e32 v69, 0x3fb8aa3b, v48
	v_mul_f32_e32 v72, 0xbfb8aa3b, v48
	v_sub_f32_e32 v48, v49, v48
	v_sub_f32_e32 v21, v24, v21
	v_mul_f32_e32 v73, 0x3fb8aa3b, v16
	v_mul_f32_e32 v74, 0xbfb8aa3b, v16
	v_sub_f32_e32 v16, v17, v16
	v_exp_f32_e32 v69, v69
	v_mul_f32_e32 v48, 0x3fb8aa3b, v48
	v_mul_f32_e32 v21, 0x3fb8aa3b, v21
	v_mul_f32_e32 v16, 0x3fb8aa3b, v16
	v_exp_f32_e32 v72, v72
	v_exp_f32_e32 v48, v48
	v_exp_f32_e32 v21, v21
	v_exp_f32_e32 v73, v73
	v_exp_f32_e32 v74, v74
	v_exp_f32_e32 v16, v16
	v_mul_f32_e32 v24, v78, v53
	v_mul_f32_e32 v1, v1, v53
	v_mul_f32_e32 v67, v68, v67
	v_mul_f32_e32 v39, v39, v69
	v_mul_f32_e32 v69, v24, v100
	v_mul_f32_e32 v20, v24, v20
	v_mul_f32_e32 v24, v1, v101
	v_mul_f32_e32 v25, v68, v25
	v_mul_f32_e32 v49, v67, v72
	v_mul_f32_e32 v68, v35, v72
	v_mul_f32_e32 v67, v67, v48
	v_mul_f32_e32 v35, v35, v48
	v_mul_f32_e32 v48, v66, v21
	v_mul_f32_e32 v21, v34, v21
	v_mul_f32_e32 v34, 0x3fb8aa3b, v45
	v_mul_f32_e32 v1, v1, v46
	v_mul_f32_e32 v17, v83, v73
	v_mul_f32_e32 v46, v24, v74
	v_mul_f32_e32 v73, v24, v16
	v_mul_f32_e32 v24, v36, v53
	s_waitcnt lgkmcnt(1)
	v_mul_f32_e32 v36, 0x3fb8aa3b, v50
	v_exp_f32_e32 v34, v34
	v_mul_f32_e32 v66, 0xbfb8aa3b, v45
	v_exp_f32_e32 v36, v36
	v_mul_f32_e32 v53, 0xbfb8aa3b, v50
	v_exp_f32_e32 v66, v66
	v_exp_f32_e32 v53, v53
	v_mul_f32_e32 v47, v24, v47
	v_mul_f32_e32 v34, v82, v34
	v_mul_f32_e32 v31, v24, v31
	v_mul_f32_e32 v36, v27, v36
	v_cvt_pk_bf16_f32 v24, v20, v1
	v_cvt_pk_bf16_f32 v25, v52, v25
	v_cvt_pk_bf16_f32 v26, v26, v40
	v_cvt_pk_bf16_f32 v27, v37, v47
	v_mul_f32_e32 v72, v66, v69
	s_waitcnt lgkmcnt(0)
	v_sub_f32_e32 v50, v51, v50
	v_mul_f32_e32 v51, v31, v53
	ds_write_b128 v169, v[24:27]
	v_cvt_pk_bf16_f32 v24, v34, v17
	v_cvt_pk_bf16_f32 v25, v38, v39
	v_cvt_pk_bf16_f32 v26, v44, v55
	v_cvt_pk_bf16_f32 v27, v56, v36
	v_mul_f32_e32 v66, v70, v66
	v_mul_f32_e32 v45, v71, v74
	v_mul_f32_e32 v69, v41, v69
	v_mul_f32_e32 v53, v29, v53
	ds_write_b128 v169, v[24:27] offset:9216
	v_cvt_pk_bf16_f32 v24, v72, v46
	v_cvt_pk_bf16_f32 v25, v57, v49
	v_cvt_pk_bf16_f32 v26, v54, v59
	v_cvt_pk_bf16_f32 v27, v64, v51
	v_mul_f32_e32 v41, v70, v41
	ds_write_b128 v169, v[24:27] offset:18432
	v_cvt_pk_bf16_f32 v24, v66, v45
	v_cvt_pk_bf16_f32 v25, v63, v68
	v_cvt_pk_bf16_f32 v26, v62, v58
	v_cvt_pk_bf16_f32 v27, v65, v53
	v_cvt_pk_bf16_f32 v1, v69, s0
	v_add_u32_e32 v17, 0, v139
	ds_write_b128 v169, v[24:27] offset:27648
	ds_write_b16 v17, v1 offset:36864
	v_cvt_pk_bf16_f32 v1, v41, s0
	ds_write_b16 v17, v1 offset:46080
	v_cvt_pk_bf16_f32 v1, v32, s0
	v_mul_f32_e32 v16, v71, v16
	ds_write_b16 v17, v1 offset:55296
	v_cvt_pk_bf16_f32 v1, v73, s0
	ds_write_b16 v170, v1 offset:36864
	v_cvt_pk_bf16_f32 v1, v16, s0
	ds_write_b16 v170, v1 offset:46080
	v_cvt_pk_bf16_f32 v1, v33, s0
	ds_write_b16 v170, v1 offset:55296
	v_cvt_pk_bf16_f32 v1, v48, s0
	ds_write_b16 v171, v1 offset:36864
	v_cvt_pk_bf16_f32 v1, v21, s0
	ds_write_b16 v171, v1 offset:46080
	v_cvt_pk_bf16_f32 v1, v22, s0
	ds_write_b16 v171, v1 offset:55296
	v_cvt_pk_bf16_f32 v1, v67, s0
	ds_write_b16 v172, v1 offset:36864
	v_cvt_pk_bf16_f32 v1, v35, s0
	ds_write_b16 v172, v1 offset:46080
	v_cvt_pk_bf16_f32 v1, v23, s0
	ds_write_b16 v172, v1 offset:55296
	v_cvt_pk_bf16_f32 v1, v60, s0
	ds_write_b16 v173, v1 offset:36864
	v_cvt_pk_bf16_f32 v1, v42, s0
	ds_write_b16 v173, v1 offset:46080
	v_cvt_pk_bf16_f32 v1, v18, s0
	v_mul_f32_e32 v50, 0x3fb8aa3b, v50
	ds_write_b16 v173, v1 offset:55296
	v_cvt_pk_bf16_f32 v1, v61, s0
	v_exp_f32_e32 v50, v50
	ds_write_b16 v174, v1 offset:36864
	v_cvt_pk_bf16_f32 v1, v43, s0
	ds_write_b16 v174, v1 offset:46080
	v_cvt_pk_bf16_f32 v1, v19, s0
	ds_write_b16 v174, v1 offset:55296
	v_cvt_pk_bf16_f32 v1, v30, s0
	ds_write_b16 v175, v1 offset:36864
	v_cvt_pk_bf16_f32 v1, v28, s0
	v_mul_f32_e32 v31, v31, v50
	ds_write_b16 v175, v1 offset:46080
	v_cvt_pk_bf16_f32 v1, v14, s0
	v_mul_f32_e32 v29, v29, v50
	ds_write_b16 v175, v1 offset:55296
	v_cvt_pk_bf16_f32 v1, v31, s0
	ds_write_b16 v177, v1 offset:36864
	v_cvt_pk_bf16_f32 v1, v29, s0
	ds_write_b16 v177, v1 offset:46080
	v_cvt_pk_bf16_f32 v1, v15, s0
	ds_write_b16 v177, v1 offset:55296
	s_mov_b64 s[0:1], 0
	v_mov_b32_e32 v1, v161
	v_mov_b32_e32 v14, v160

.LBB0_1278:
	s_add_i32 s1, s20, s14
	s_waitcnt vmcnt(0)
	v_lshlrev_b32_e32 v62, 16, v38
	v_lshlrev_b32_e32 v96, 16, v26
	s_cmp_lt_i32 s1, 0x8000
	v_lshlrev_b32_e32 v54, 16, v41
	v_and_b32_e32 v55, 0xffff0000, v41
	v_lshlrev_b32_e32 v48, 16, v37
	v_and_b32_e32 v49, 0xffff0000, v37
	v_lshlrev_b32_e32 v46, 16, v33
	v_and_b32_e32 v47, 0xffff0000, v33
	v_lshlrev_b32_e32 v56, 16, v40
	v_and_b32_e32 v57, 0xffff0000, v40
	v_lshlrev_b32_e32 v40, 16, v36
	v_and_b32_e32 v41, 0xffff0000, v36
	v_lshlrev_b32_e32 v36, 16, v32
	v_and_b32_e32 v37, 0xffff0000, v32
	v_lshlrev_b32_e32 v60, 16, v39
	v_and_b32_e32 v61, 0xffff0000, v39
	v_lshlrev_b32_e32 v50, 16, v35
	v_and_b32_e32 v51, 0xffff0000, v35
	v_lshlrev_b32_e32 v32, 16, v31
	v_and_b32_e32 v33, 0xffff0000, v31
	v_and_b32_e32 v63, 0xffff0000, v38
	v_lshlrev_b32_e32 v38, 16, v34
	v_and_b32_e32 v39, 0xffff0000, v34
	v_lshlrev_b32_e32 v34, 16, v30
	v_and_b32_e32 v35, 0xffff0000, v30
	v_lshlrev_b32_e32 v64, 16, v29
	v_and_b32_e32 v65, 0xffff0000, v29
	v_lshlrev_b32_e32 v52, 16, v25
	v_and_b32_e32 v53, 0xffff0000, v25
	v_lshlrev_b32_e32 v30, 16, v21
	v_and_b32_e32 v31, 0xffff0000, v21
	v_lshlrev_b32_e32 v92, 16, v28
	v_and_b32_e32 v93, 0xffff0000, v28
	v_lshlrev_b32_e32 v28, 16, v24
	v_and_b32_e32 v29, 0xffff0000, v24
	v_lshlrev_b32_e32 v24, 16, v20
	v_and_b32_e32 v25, 0xffff0000, v20
	v_lshlrev_b32_e32 v94, 16, v27
	v_and_b32_e32 v95, 0xffff0000, v27
	v_lshlrev_b32_e32 v58, 16, v23
	v_and_b32_e32 v59, 0xffff0000, v23
	v_lshlrev_b32_e32 v20, 16, v19
	v_and_b32_e32 v21, 0xffff0000, v19
	v_and_b32_e32 v97, 0xffff0000, v26
	v_lshlrev_b32_e32 v26, 16, v22
	v_and_b32_e32 v27, 0xffff0000, v22
	v_lshlrev_b32_e32 v22, 16, v18
	v_and_b32_e32 v23, 0xffff0000, v18
	v_add_f32_e32 v18, 0, v62
	v_add_f32_e32 v19, 0, v96
	s_cselect_b64 s[4:5], -1, 0
	v_add_f32_e32 v18, v18, v63
	v_add_f32_e32 v19, v19, v97
	s_and_b64 vcc, s[4:5], exec
	v_add_f32_e32 v18, v18, v60
	v_add_f32_e32 v19, v19, v94
	s_cselect_b32 s0, s1, s20
	v_add_f32_e32 v18, v18, v61
	v_add_f32_e32 v19, v19, v95
	s_mov_b32 s20, s1
	s_ashr_i32 s1, s0, 31
	s_or_b32 s4, s0, 1
	v_add_f32_e32 v18, v18, v56
	v_add_f32_e32 v19, v19, v92
	s_lshl_b64 s[0:1], s[0:1], 10
	s_ashr_i32 s5, s4, 31
	v_add_f32_e32 v68, v18, v57
	v_add_f32_e32 v69, v19, v93
	v_or_b32_e32 v18, s0, v67
	v_mov_b32_e32 v19, s1
	s_lshl_b64 s[0:1], s[4:5], 10
	v_add_f32_e32 v68, v68, v54
	v_add_f32_e32 v69, v69, v64
	v_lshl_add_u64 v[76:77], s[8:9], 0, v[18:19]
	v_lshl_add_u64 v[78:79], s[12:13], 0, v[18:19]
	v_lshl_add_u64 v[18:19], s[10:11], 0, v[18:19]
	v_or_b32_e32 v80, s0, v67
	v_mov_b32_e32 v81, s1
	v_add_f32_e32 v104, v68, v55
	v_add_f32_e32 v105, v69, v65
	global_load_dwordx4 v[68:71], v[76:77], off
	global_load_dwordx4 v[72:75], v[78:79], off
	v_lshl_add_u64 v[98:99], s[8:9], 0, v[80:81]
	v_lshl_add_u64 v[100:101], s[12:13], 0, v[80:81]
	v_lshl_add_u64 v[102:103], s[10:11], 0, v[80:81]
	global_load_dwordx4 v[76:79], v[18:19], off
	global_load_dwordx4 v[80:83], v[98:99], off
	global_load_dwordx4 v[84:87], v[100:101], off
	global_load_dwordx4 v[88:91], v[102:103], off
	s_nop 1
	v_add_f32_dpp v18, v104, v104 quad_perm:[1,0,3,2] row_mask:0xf bank_mask:0xf
	v_add_f32_dpp v19, v105, v105 quad_perm:[1,0,3,2] row_mask:0xf bank_mask:0xf
	s_nop 1
	v_add_f32_dpp v18, v18, v18 quad_perm:[2,3,0,1] row_mask:0xf bank_mask:0xf
	v_add_f32_dpp v19, v19, v19 quad_perm:[2,3,0,1] row_mask:0xf bank_mask:0xf
	s_nop 1
	v_add_f32_dpp v18, v18, v18 row_half_mirror row_mask:0xf bank_mask:0xf
	v_add_f32_dpp v19, v19, v19 row_half_mirror row_mask:0xf bank_mask:0xf
	s_nop 1
	v_mul_f32_e32 v18, 0x3c800000, v18
	v_mul_f32_e32 v98, 0x3c800000, v19
	v_pk_add_f32 v[62:63], v[62:63], v[18:19] op_sel_hi:[1,0] neg_lo:[0,1] neg_hi:[0,1]
	v_pk_add_f32 v[60:61], v[60:61], v[18:19] op_sel_hi:[1,0] neg_lo:[0,1] neg_hi:[0,1]
	v_pk_add_f32 v[56:57], v[56:57], v[18:19] op_sel_hi:[1,0] neg_lo:[0,1] neg_hi:[0,1]
	v_pk_add_f32 v[18:19], v[54:55], v[18:19] op_sel_hi:[1,0] neg_lo:[0,1] neg_hi:[0,1]
	v_pk_add_f32 v[54:55], v[96:97], v[98:99] op_sel_hi:[1,0] neg_lo:[0,1] neg_hi:[0,1]
	v_pk_add_f32 v[94:95], v[94:95], v[98:99] op_sel_hi:[1,0] neg_lo:[0,1] neg_hi:[0,1]
	v_pk_mul_f32 v[96:97], v[62:63], v[62:63]
	v_pk_mul_f32 v[104:105], v[54:55], v[54:55]
	v_pk_add_f32 v[92:93], v[92:93], v[98:99] op_sel_hi:[1,0] neg_lo:[0,1] neg_hi:[0,1]
	v_pk_add_f32 v[64:65], v[64:65], v[98:99] op_sel_hi:[1,0] neg_lo:[0,1] neg_hi:[0,1]
	v_pk_mul_f32 v[98:99], v[60:61], v[60:61]
	v_pk_mul_f32 v[106:107], v[94:95], v[94:95]
	v_mov_b32_e32 v112, v104
	v_mov_b32_e32 v113, v96
	v_mov_b32_e32 v96, v105
	v_mov_b32_e32 v104, v106
	v_mov_b32_e32 v105, v98
	v_pk_add_f32 v[96:97], v[112:113], v[96:97]
	v_pk_mul_f32 v[100:101], v[56:57], v[56:57]
	v_pk_mul_f32 v[108:109], v[92:93], v[92:93]
	v_mov_b32_e32 v98, v107
	v_pk_add_f32 v[96:97], v[104:105], v[96:97]
	v_mov_b32_e32 v106, v108
	v_mov_b32_e32 v107, v100
	v_pk_add_f32 v[96:97], v[98:99], v[96:97]
	v_pk_mul_f32 v[102:103], v[18:19], v[18:19]
	v_pk_mul_f32 v[110:111], v[64:65], v[64:65]
	v_mov_b32_e32 v100, v109
	v_pk_add_f32 v[96:97], v[106:107], v[96:97]
	v_mov_b32_e32 v108, v110
	v_mov_b32_e32 v109, v102
	v_pk_add_f32 v[96:97], v[100:101], v[96:97]
	v_mov_b32_e32 v102, v111
	v_pk_add_f32 v[96:97], v[108:109], v[96:97]
	s_nop 0
	v_pk_add_f32 v[96:97], v[102:103], v[96:97]
	s_nop 1
	v_add_f32_dpp v96, v96, v96 quad_perm:[1,0,3,2] row_mask:0xf bank_mask:0xf
	v_add_f32_dpp v97, v97, v97 quad_perm:[1,0,3,2] row_mask:0xf bank_mask:0xf
	s_nop 1
	v_add_f32_dpp v96, v96, v96 quad_perm:[2,3,0,1] row_mask:0xf bank_mask:0xf
	v_add_f32_dpp v97, v97, v97 quad_perm:[2,3,0,1] row_mask:0xf bank_mask:0xf
	s_nop 1
	v_add_f32_dpp v96, v96, v96 row_half_mirror row_mask:0xf bank_mask:0xf
	v_add_f32_dpp v97, v97, v97 row_half_mirror row_mask:0xf bank_mask:0xf
	s_nop 1
	s_nop 0
	v_pk_fma_f32 v[96:97], v[96:97], s[18:19], v[44:45] op_sel_hi:[1,0,0]
	s_nop 0
	v_mul_f32_e32 v98, 0x4b800000, v97
	v_mul_f32_e32 v99, 0x4b800000, v96
	v_cmp_gt_f32_e64 s[0:1], s2, v96
	v_cmp_gt_f32_e64 s[4:5], s2, v97
	s_nop 0
	v_cndmask_b32_e64 v96, v96, v99, s[0:1]
	v_cndmask_b32_e64 v97, v97, v98, s[4:5]
	v_rsq_f32_e32 v97, v97
	v_rsq_f32_e32 v98, v96
	v_mul_f32_e32 v96, 0x45800000, v97
	v_mul_f32_e32 v99, 0x45800000, v98
	v_cndmask_b32_e64 v96, v97, v96, s[4:5]
	v_cndmask_b32_e64 v98, v98, v99, s[0:1]
	v_pk_mul_f32 v[62:63], v[62:63], v[96:97] op_sel_hi:[1,0]
	v_pk_mul_f32 v[60:61], v[60:61], v[96:97] op_sel_hi:[1,0]
	v_pk_mul_f32 v[56:57], v[56:57], v[96:97] op_sel_hi:[1,0]
	v_pk_mul_f32 v[18:19], v[18:19], v[96:97] op_sel_hi:[1,0]
	v_pk_mul_f32 v[54:55], v[54:55], v[98:99] op_sel_hi:[1,0]
	v_pk_mul_f32 v[94:95], v[94:95], v[98:99] op_sel_hi:[1,0]
	v_pk_mul_f32 v[92:93], v[92:93], v[98:99] op_sel_hi:[1,0]
	v_pk_mul_f32 v[64:65], v[64:65], v[98:99] op_sel_hi:[1,0]
	v_pk_fma_f32 v[62:63], v[10:11], v[62:63], v[2:3]
	v_pk_fma_f32 v[60:61], v[12:13], v[60:61], v[4:5]
	v_pk_fma_f32 v[56:57], v[14:15], v[56:57], v[6:7]
	v_pk_fma_f32 v[18:19], v[16:17], v[18:19], v[8:9]
	v_pk_fma_f32 v[54:55], v[10:11], v[54:55], v[2:3]
	v_pk_fma_f32 v[94:95], v[12:13], v[94:95], v[4:5]
	v_pk_fma_f32 v[92:93], v[14:15], v[92:93], v[6:7]
	v_pk_fma_f32 v[64:65], v[16:17], v[64:65], v[8:9]
	v_pk_add_f32 v[38:39], v[62:63], v[38:39]
	v_pk_add_f32 v[50:51], v[60:61], v[50:51]
	v_pk_add_f32 v[40:41], v[56:57], v[40:41]
	v_pk_add_f32 v[18:19], v[18:19], v[48:49]
	v_pk_add_f32 v[26:27], v[54:55], v[26:27]
	v_pk_add_f32 v[48:49], v[94:95], v[58:59]
	v_pk_add_f32 v[28:29], v[92:93], v[28:29]
	v_pk_add_f32 v[52:53], v[64:65], v[52:53]
	v_pk_mul_f32 v[34:35], v[38:39], v[34:35]
	v_pk_mul_f32 v[32:33], v[50:51], v[32:33]
	v_pk_mul_f32 v[36:37], v[40:41], v[36:37]
	v_pk_mul_f32 v[38:39], v[18:19], v[46:47]
	v_pk_mul_f32 v[22:23], v[26:27], v[22:23]
	v_pk_mul_f32 v[26:27], v[48:49], v[20:21]
	v_pk_mul_f32 v[24:25], v[28:29], v[24:25]
	v_pk_mul_f32 v[28:29], v[52:53], v[30:31]
	v_cvt_pk_bf16_f32 v18, v34, v35
	v_cvt_pk_bf16_f32 v19, v32, v33
	v_cvt_pk_bf16_f32 v20, v36, v37
	v_cvt_pk_bf16_f32 v21, v38, v39
	v_cvt_pk_bf16_f32 v22, v22, v23
	v_cvt_pk_bf16_f32 v23, v26, v27
	v_cvt_pk_bf16_f32 v24, v24, v25
	v_cvt_pk_bf16_f32 v25, v28, v29
	global_store_dwordx4 v[42:43], v[18:21], off offset:-2048
	global_store_dwordx4 v[42:43], v[22:25], off
	s_waitcnt vmcnt(5)
	v_mov_b64_e32 v[30:31], v[76:77]
	v_mov_b64_e32 v[34:35], v[72:73]
	v_mov_b64_e32 v[38:39], v[68:69]
	s_waitcnt vmcnt(2)
	v_mov_b64_e32 v[18:19], v[88:89]
	v_mov_b64_e32 v[22:23], v[84:85]
	v_mov_b64_e32 v[26:27], v[80:81]
	v_lshl_add_u64 v[42:43], v[42:43], 0, s[16:17]
	v_mov_b64_e32 v[32:33], v[78:79]
	v_mov_b64_e32 v[36:37], v[74:75]
	v_mov_b64_e32 v[40:41], v[70:71]
	v_mov_b64_e32 v[20:21], v[90:91]
	v_mov_b64_e32 v[24:25], v[86:87]
	v_mov_b64_e32 v[28:29], v[82:83]
	s_cbranch_vccnz .LBB0_1278
